# mLSTM/LRU sync points moved to chunks 56/80
# baseline (speedup 1.0000x reference)
; template <bool INSYNC> DI void mlstm_phase(const Ctx& C, const bf16* PROJ, const f32x4* TAB, const bf16* PP, bf16* HF, bf16* HB, const XcdBarrier& xbar) {
;     ...
;         for (int c = 0; c < SEQ / 64; ++c) {
;             if (INSYNC && (c == 43 || c == 86)) xcd_barrier(xbar);
.LBB0_1403:
	s_mov_b32 s35, s22
	s_cmpk_lt_i32 s22, 0x50
	s_cbranch_scc1 .LBB0_1405
	s_cmpk_eq_i32 s35, 0x50
	s_cselect_b64 s[20:21], -1, 0
	s_cbranch_execz .LBB0_1406
	s_branch .LBB0_1407

; template <bool INSYNC> DI void mlstm_phase(const Ctx& C, const bf16* PROJ, const f32x4* TAB, const bf16* PP, bf16* HF, bf16* HB, const XcdBarrier& xbar) {
;     ...
;             if (INSYNC && (c == 43 || c == 86)) xcd_barrier(xbar);
.LBB0_1406:
	s_cmp_eq_u32 s35, 56
	s_cselect_b64 s[20:21], -1, 0
